# all 13 GEMM call prologues: second LDS-DMA batch issued before the wait on the first (vmcnt 2 -> 8, same barriers)
# baseline (speedup 1.0000x reference)
; #define PG8_STAGE(bufoff, gbase, voff) do { _Pragma("unroll") for (int _i = 0; _i < 2; ++_i) \
;         __builtin_amdgcn_global_load_lds((const unsigned*)((const char*)(gbase) + (voff)[_i]), (LAS unsigned*)(lds + (bufoff) + ldsw + _i * 8192), 16, 0, 0); } while (0)
; #define PG8_WAIT_V(n) asm volatile("s_waitcnt vmcnt(" #n ")" ::: "memory")
; #define PG8_BAR __builtin_amdgcn_s_barrier()
; #define lane lane_id()
; template <class Epi, class Sched>
; __device__ __forceinline__ void gemm_phase(LAS unsigned char* lds, const Gemm g, const Sched& S, const Epi& E, int wave_id) {
;     ...
;     const int wid = wave_id, lane = tid & 63, wr = wid >> 2, wc = wid & 3, fr = lane & 15, fq = lane >> 4;
;     const int K = g.K, nt = K / BK;
;     unsigned voffA[2], voffB[2];
; #pragma unroll
;     for (int i = 0; i < 2; ++i) { int R, C; stage_rc(tid * 16 + i * 8192, R, C); const int Rb = (R & ~31) + perm32(R & 31);
;         voffA[i] = (unsigned)(R * g.lda + C) * 2u; voffB[i] = (unsigned)(Rb * g.ldb + C) * 2u; }
;     const size_t kstep = (size_t)(BK * 2);
;     const size_t hstepA = (size_t)HALF * g.lda * 2, hstepB = (size_t)HALF * g.ldb * 2;
;     const size_t tstepA = 2 * hstepA, tstepB = 2 * hstepB;
;     const unsigned ldsw = (unsigned)wid * 1024u;
;     const int aoff = lds_byte(wr * 64 + fr, fq * 8), boff = lds_byte(wc * 32 + fr, fq * 8);
;     ...
;     PG8_STAGE(PG8_SB(0, 0), cB, voffB); PG8_STAGE(PG8_SB(0, 1), cB + hstepB, voffB); PG8_STAGE(PG8_SA(0, 0), cA, voffA); PG8_STAGE(PG8_SA(0, 1), cA + hstepA, voffA);
;     if (wr == 1) PG8_BAR;
;     PG8_WAIT_V(2); PG8_BAR;
;     PG8_STAGE(PG8_SB(1, 0), cB + kstep, voffB); PG8_STAGE(PG8_SA(1, 0), cA + kstep, voffA); PG8_STAGE(PG8_SB(1, 1), cB + hstepB + kstep, voffB);
;     PG8_WAIT_V(6); PG8_BAR;
.LBB0_246:
	s_lshl_b32 s4, s97, 5
	s_mov_b64 s[22:23], 0x80
	s_and_b32 s7, s4, 0x60
	s_add_i32 m0, s55, 0x18000
	v_lshl_add_u64 v[6:7], v[6:7], 0, s[22:23]
	s_lshl_b32 s61, s2, 6
	s_lshl_b32 s2, s2, 13
	s_lshl_b32 s9, s7, 7
	global_load_lds_dwordx4 v[6:7], off
	v_lshl_add_u64 v[4:5], v[4:5], 0, s[22:23]
	s_add_i32 m0, s55, 0x1a000
	s_add_i32 s62, s55, 0x8000
	s_add_i32 s63, s55, 0xa000
	global_load_lds_dwordx4 v[4:5], off
	v_lshl_add_u64 v[0:1], v[0:1], 0, s[22:23]
	s_mov_b32 m0, s62
	s_add_u32 s4, s12, 0x40080
	global_load_lds_dwordx4 v[0:1], off
	v_lshl_add_u64 v[0:1], v[2:3], 0, s[22:23]
	s_mov_b32 m0, s63
	s_addc_u32 s5, s13, 0
	global_load_lds_dwordx4 v[0:1], off
	s_add_i32 m0, s55, 0x1c000
	v_lshl_add_u64 v[0:1], s[4:5], 0, v[146:147]
	global_load_lds_dwordx4 v[0:1], off
	v_lshl_add_u64 v[0:1], s[4:5], 0, v[150:151]
	s_add_i32 m0, s55, 0x1e000
	v_and_b32_e32 v167, 15, v8
	global_load_lds_dwordx4 v[0:1], off
	s_waitcnt vmcnt(8)
	s_barrier
	v_lshrrev_b32_e32 v0, 1, v8
	v_and_b32_e32 v2, 24, v0
	v_lshlrev_b32_e32 v0, 1, v2
	v_lshlrev_b32_e32 v1, 2, v8
	v_lshl_or_b32 v0, v167, 6, v0
	v_and_b32_e32 v1, 32, v1
	s_cmpk_lt_u32 s80, 0x100
	v_bitop3_b32 v3, v0, s2, v1 bitop3:0xde
	s_cselect_b64 s[24:25], -1, 0
	s_lshl_b32 s2, s7, 2
	s_add_u32 s4, s92, s2
	s_addc_u32 s5, s93, 0
	v_lshlrev_b32_e32 v152, 2, v2
	v_bitop3_b32 v171, v0, s9, v1 bitop3:0xde
	v_lshl_add_u64 v[0:1], s[4:5], 0, v[152:153]
	s_mov_b64 s[4:5], 0x1f4c0000
	v_lshlrev_b32_e32 v152, 5, v167
	v_lshl_add_u64 v[154:155], v[0:1], 0, s[4:5]
	s_add_u32 s26, s92, 0x1f400000
	v_lshl_add_u64 v[0:1], s[92:93], 0, v[152:153]
	v_and_b32_e32 v152, 16, v8
	s_addc_u32 s27, s93, 0
	v_lshl_add_u64 v[0:1], v[0:1], 0, v[152:153]
	s_mov_b64 s[4:5], 0x17400000
	s_add_u32 s28, s92, 0x1a400000
	v_lshl_add_u64 v[156:157], v[0:1], 0, s[4:5]
	v_lshlrev_b32_e32 v0, 14, v9
	s_addc_u32 s29, s93, 0
	v_and_b32_e32 v0, 0xffff8000, v0
	s_add_u32 s30, s92, 0xf400000
	v_lshl_add_u32 v0, v10, 11, v0
	v_and_b32_e32 v1, 1, v9
	s_addc_u32 s31, s93, 0
	v_lshl_or_b32 v0, v1, 6, v0
	s_add_u32 s34, s92, 0x13400000
	v_lshl_add_u32 v158, v11, 1, v0
	v_lshlrev_b32_e32 v0, 14, v12
	s_addc_u32 s35, s93, 0
	v_and_b32_e32 v0, 0xffff8000, v0
	s_waitcnt vmcnt(6)
	s_add_u32 s36, s92, 0x7400000
	v_lshl_add_u32 v0, v13, 11, v0
	v_and_b32_e32 v1, 1, v12
	v_or_b32_e32 v173, s7, v2
	s_addc_u32 s37, s93, 0
	v_readlane_b32 s4, v255, 1
	v_lshl_or_b32 v0, v1, 6, v0
	s_add_i32 s67, 0, 0x10000
	s_add_i32 s72, 0, 0x14000
	v_or_b32_e32 v175, 0xffffee00, v173
	v_or_b32_e32 v177, 0xfffff000, v173
	v_or_b32_e32 v179, 0xffffee80, v173
	v_or_b32_e32 v181, 0xfffff080, v173
	s_ashr_i32 s64, s4, 31
	s_mov_b32 s65, s4
	s_ashr_i32 s66, s66, 31
	v_mov_b32_e32 v159, v153
	v_lshl_add_u32 v160, v14, 1, v0
	v_mov_b32_e32 v161, v153
	v_mov_b64_e32 v[162:163], 0xa00
	v_mov_b64_e32 v[164:165], 0x9ff
	v_add_u32_e32 v183, s67, v171
	v_add_u32_e32 v190, s72, v171
	v_add_u32_e32 v191, 0, v3
	s_movk_i32 s73, 0x300
	s_mov_b32 s74, 0x800000
	s_mov_b32 s75, 0x3f317217
	s_mov_b32 s76, 0x7f800000
	v_mov_b32_e32 v192, 0x41b17218
	s_mov_b32 s77, 0
	s_barrier
	v_readlane_b32 s5, v255, 2
	s_branch .LBB0_249

; #define PG8_STAGE(bufoff, gbase, voff) do { _Pragma("unroll") for (int _i = 0; _i < 2; ++_i) \
;         __builtin_amdgcn_global_load_lds((const unsigned*)((const char*)(gbase) + (voff)[_i]), (LAS unsigned*)(lds + (bufoff) + ldsw + _i * 8192), 16, 0, 0); } while (0)
; #define PG8_WAIT_V(n) asm volatile("s_waitcnt vmcnt(" #n ")" ::: "memory")
; #define PG8_BAR __builtin_amdgcn_s_barrier()
; #define lane lane_id()
; template <class Epi, class Sched>
; __device__ __forceinline__ void gemm_phase(LAS unsigned char* lds, const Gemm g, const Sched& S, const Epi& E, int wave_id) {
;     ...
;     const int wid = wave_id, lane = tid & 63, wr = wid >> 2, wc = wid & 3, fr = lane & 15, fq = lane >> 4;
;     const int K = g.K, nt = K / BK;
;     unsigned voffA[2], voffB[2];
; #pragma unroll
;     for (int i = 0; i < 2; ++i) { int R, C; stage_rc(tid * 16 + i * 8192, R, C); const int Rb = (R & ~31) + perm32(R & 31);
;         voffA[i] = (unsigned)(R * g.lda + C) * 2u; voffB[i] = (unsigned)(Rb * g.ldb + C) * 2u; }
;     const size_t kstep = (size_t)(BK * 2);
;     const size_t hstepA = (size_t)HALF * g.lda * 2, hstepB = (size_t)HALF * g.ldb * 2;
;     const size_t tstepA = 2 * hstepA, tstepB = 2 * hstepB;
;     const unsigned ldsw = (unsigned)wid * 1024u;
;     const int aoff = lds_byte(wr * 64 + fr, fq * 8), boff = lds_byte(wc * 32 + fr, fq * 8);
;     ...
;     PG8_STAGE(PG8_SB(0, 0), cB, voffB); PG8_STAGE(PG8_SB(0, 1), cB + hstepB, voffB); PG8_STAGE(PG8_SA(0, 0), cA, voffA); PG8_STAGE(PG8_SA(0, 1), cA + hstepA, voffA);
;     if (wr == 1) PG8_BAR;
;     PG8_WAIT_V(2); PG8_BAR;
;     PG8_STAGE(PG8_SB(1, 0), cB + kstep, voffB); PG8_STAGE(PG8_SA(1, 0), cA + kstep, voffA); PG8_STAGE(PG8_SB(1, 1), cB + hstepB + kstep, voffB);
;     PG8_WAIT_V(6); PG8_BAR;
.LBB0_662:
	s_lshl_b32 s6, s97, 5
	s_and_b32 s14, s6, 0x60
	s_mov_b64 s[6:7], 0x80
	v_readlane_b32 s16, v255, 1
	s_add_i32 m0, s31, 0x18000
	v_lshl_add_u64 v[6:7], v[6:7], 0, s[6:7]
	s_lshl_b32 s12, s9, 13
	s_lshl_b32 s13, s14, 7
	s_ashr_i32 s51, s16, 31
	global_load_lds_dwordx4 v[6:7], off
	v_lshl_add_u64 v[4:5], v[4:5], 0, s[6:7]
	s_add_i32 m0, s31, 0x1a000
	s_add_i32 s52, s31, 0x8000
	s_add_i32 s53, s31, 0xa000
	global_load_lds_dwordx4 v[4:5], off
	v_lshl_add_u64 v[0:1], v[0:1], 0, s[6:7]
	s_mov_b32 m0, s52
	s_add_u32 s10, s36, 0x40080
	global_load_lds_dwordx4 v[0:1], off
	v_lshl_add_u64 v[0:1], v[2:3], 0, s[6:7]
	s_mov_b32 m0, s53
	s_addc_u32 s11, s37, 0
	global_load_lds_dwordx4 v[0:1], off
	s_add_i32 m0, s31, 0x1c000
	v_lshl_add_u64 v[0:1], s[10:11], 0, v[130:131]
	global_load_lds_dwordx4 v[0:1], off
	v_lshl_add_u64 v[0:1], s[10:11], 0, v[134:135]
	s_add_i32 m0, s31, 0x1e000
	s_cmpk_lt_u32 s80, 0x100
	global_load_lds_dwordx4 v[0:1], off
	s_waitcnt vmcnt(8)
	s_barrier
	v_lshrrev_b32_e32 v1, 1, v8
	v_and_b32_e32 v1, 24, v1
	v_and_b32_e32 v0, 15, v8
	v_lshlrev_b32_e32 v2, 1, v1
	v_lshl_or_b32 v158, s9, 6, v0
	v_lshl_or_b32 v0, v0, 6, v2
	v_lshlrev_b32_e32 v2, 2, v8
	v_and_b32_e32 v2, 32, v2
	v_bitop3_b32 v3, v0, s12, v2 bitop3:0xde
	v_bitop3_b32 v159, v0, s13, v2 bitop3:0xde
	v_lshlrev_b32_e32 v0, 14, v9
	v_and_b32_e32 v0, 0xffff8000, v0
	v_or_b32_e32 v160, s14, v1
	v_lshl_add_u32 v0, v10, 11, v0
	v_and_b32_e32 v1, 1, v9
	v_lshl_or_b32 v0, v1, 6, v0
	s_sext_i32_i8 s60, s8
	s_cselect_b64 s[8:9], -1, 0
	s_add_u32 s10, s92, 0x1f400000
	v_lshl_add_u32 v136, v11, 1, v0
	v_lshlrev_b32_e32 v0, 14, v12
	s_addc_u32 s11, s93, 0
	v_and_b32_e32 v0, 0xffff8000, v0
	s_waitcnt vmcnt(6)
	s_add_u32 s12, s92, 0xb400000
	v_lshl_add_u32 v0, v13, 11, v0
	v_and_b32_e32 v1, 1, v12
	s_addc_u32 s13, s93, 0
	v_lshl_or_b32 v0, v1, 6, v0
	s_add_i32 s55, 0, 0x10000
	s_add_i32 s58, 0, 0x14000
	s_mov_b32 s54, s16
	v_mov_b32_e32 v137, v131
	v_lshl_add_u32 v138, v14, 1, v0
	v_mov_b32_e32 v139, v131
	v_add_u32_e32 v161, s55, v159
	v_add_u32_e32 v162, s58, v159
	v_add_u32_e32 v163, 0, v3
	s_mov_b32 s14, 0x437f0000
	s_mov_b32 s59, 0xb400000
	v_mov_b64_e32 v[140:141], 0x3ff
	v_readlane_b32 s17, v255, 2
	s_barrier
	s_branch .LBB0_665

; #define PG8_STAGE(bufoff, gbase, voff) do { _Pragma("unroll") for (int _i = 0; _i < 2; ++_i) \
;         __builtin_amdgcn_global_load_lds((const unsigned*)((const char*)(gbase) + (voff)[_i]), (LAS unsigned*)(lds + (bufoff) + ldsw + _i * 8192), 16, 0, 0); } while (0)
; #define PG8_WAIT_V(n) asm volatile("s_waitcnt vmcnt(" #n ")" ::: "memory")
; #define PG8_BAR __builtin_amdgcn_s_barrier()
; #define lane lane_id()
; template <class Epi, class Sched>
; __device__ __forceinline__ void gemm_phase(LAS unsigned char* lds, const Gemm g, const Sched& S, const Epi& E, int wave_id) {
;     ...
;     const int wid = wave_id, lane = tid & 63, wr = wid >> 2, wc = wid & 3, fr = lane & 15, fq = lane >> 4;
;     const int K = g.K, nt = K / BK;
;     unsigned voffA[2], voffB[2];
; #pragma unroll
;     for (int i = 0; i < 2; ++i) { int R, C; stage_rc(tid * 16 + i * 8192, R, C); const int Rb = (R & ~31) + perm32(R & 31);
;         voffA[i] = (unsigned)(R * g.lda + C) * 2u; voffB[i] = (unsigned)(Rb * g.ldb + C) * 2u; }
;     const size_t kstep = (size_t)(BK * 2);
;     const size_t hstepA = (size_t)HALF * g.lda * 2, hstepB = (size_t)HALF * g.ldb * 2;
;     const size_t tstepA = 2 * hstepA, tstepB = 2 * hstepB;
;     const unsigned ldsw = (unsigned)wid * 1024u;
;     const int aoff = lds_byte(wr * 64 + fr, fq * 8), boff = lds_byte(wc * 32 + fr, fq * 8);
;     ...
;     PG8_STAGE(PG8_SB(0, 0), cB, voffB); PG8_STAGE(PG8_SB(0, 1), cB + hstepB, voffB); PG8_STAGE(PG8_SA(0, 0), cA, voffA); PG8_STAGE(PG8_SA(0, 1), cA + hstepA, voffA);
;     if (wr == 1) PG8_BAR;
;     PG8_WAIT_V(2); PG8_BAR;
;     PG8_STAGE(PG8_SB(1, 0), cB + kstep, voffB); PG8_STAGE(PG8_SA(1, 0), cA + kstep, voffA); PG8_STAGE(PG8_SB(1, 1), cB + hstepB + kstep, voffB);
;     PG8_WAIT_V(6); PG8_BAR;
.LBB0_688:
	s_mov_b64 s[10:11], 0x80
	s_add_i32 m0, s36, 0x18000
	v_lshl_add_u64 v[6:7], v[6:7], 0, s[10:11]
	global_load_lds_dwordx4 v[6:7], off
	v_lshl_add_u64 v[2:3], v[2:3], 0, s[10:11]
	s_add_i32 m0, s36, 0x1a000
	s_add_i32 s48, s36, 0x8000
	s_add_i32 s50, s36, 0xa000
	global_load_lds_dwordx4 v[2:3], off
	v_lshl_add_u64 v[0:1], v[0:1], 0, s[10:11]
	s_mov_b32 m0, s48
	s_add_u32 s4, s30, 0x10080
	global_load_lds_dwordx4 v[0:1], off
	v_lshl_add_u64 v[0:1], v[4:5], 0, s[10:11]
	s_mov_b32 m0, s50
	s_addc_u32 s5, s31, 0
	s_add_i32 s51, s36, 0x1c000
	global_load_lds_dwordx4 v[0:1], off
	v_lshl_add_u64 v[0:1], s[4:5], 0, v[68:69]
	s_mov_b32 m0, s51
	s_add_i32 s58, s36, 0x1e000
	global_load_lds_dwordx4 v[0:1], off
	v_lshl_add_u64 v[0:1], s[4:5], 0, v[64:65]
	s_mov_b32 m0, s58
	s_movk_i32 s4, 0x3c0
	global_load_lds_dwordx4 v[0:1], off
	s_waitcnt vmcnt(8)
	s_barrier
	v_and_b32_e32 v0, 15, v8
	v_lshrrev_b32_e32 v1, 1, v8
	v_or_b32_e32 v74, s55, v0
	v_and_b32_e32 v1, 24, v1
	v_lshlrev_b32_e32 v2, 6, v74
	v_lshlrev_b32_e32 v3, 1, v1
	v_and_or_b32 v2, v2, s4, v3
	v_lshl_or_b32 v0, v0, 6, v3
	v_lshlrev_b32_e32 v3, 2, v8
	v_and_b32_e32 v3, 32, v3
	v_bitop3_b32 v3, v0, s52, v3 bitop3:0xde
	v_or_b32_e32 v0, s53, v1
	s_cmpk_lt_u32 s80, 0x100
	v_lshlrev_b32_e32 v0, 2, v0
	v_mov_b32_e32 v1, v69
	v_readlane_b32 s16, v255, 1
	s_cselect_b64 s[4:5], -1, 0
	v_lshl_add_u64 v[0:1], s[92:93], 0, v[0:1]
	s_mov_b64 s[12:13], 0x1d400000
	s_add_i32 s59, s66, s16
	v_lshl_add_u64 v[72:73], v[0:1], 0, s[12:13]
	s_mul_i32 s13, s59, 0x30000
	s_mul_hi_i32 s12, s59, 0x30000
	s_add_u32 s13, s92, s13
	s_addc_u32 s14, s93, s12
	v_lshlrev_b32_e32 v4, 2, v74
	s_add_u32 s12, s13, 0x17400000
	v_and_b32_e32 v4, 32, v4
	s_waitcnt vmcnt(6)
	s_addc_u32 s13, s14, 0
	s_add_i32 s64, 0, 0x10000
	s_mov_b32 s22, s66
	s_add_i32 s66, 0, 0x18000
	v_bitop3_b32 v2, v2, s54, v4 bitop3:0xde
	v_readlane_b32 s17, v255, 2
	v_add_u32_e32 v75, s64, v3
	s_add_i32 s64, s64, s44
	v_cndmask_b32_e64 v0, 0, 1, s[4:5]
	v_add_u32_e32 v77, s66, v3
	s_add_i32 s66, s66, s44
	s_mul_hi_i32 s60, s16, 0x30000
	s_mul_i32 s61, s16, 0x30000
	v_add_u32_e32 v76, 0, v2
	s_add_i32 s62, s36, 0xc000
	s_add_i32 s63, s36, 0xe000
	s_mov_b64 s[14:15], 0x100
	s_add_i32 s65, s64, 0x2000
	s_mov_b64 s[16:17], 0x180
	s_add_i32 s67, s66, 0x2000
	v_cmp_ne_u32_e64 s[4:5], 1, v0
	s_mov_b32 s73, s22
	s_mov_b64 s[22:23], s[28:29]
	s_barrier
	s_branch .LBB0_691

; #define PG8_STAGE(bufoff, gbase, voff) do { _Pragma("unroll") for (int _i = 0; _i < 2; ++_i) \
;         __builtin_amdgcn_global_load_lds((const unsigned*)((const char*)(gbase) + (voff)[_i]), (LAS unsigned*)(lds + (bufoff) + ldsw + _i * 8192), 16, 0, 0); } while (0)
; #define PG8_WAIT_V(n) asm volatile("s_waitcnt vmcnt(" #n ")" ::: "memory")
; #define PG8_BAR __builtin_amdgcn_s_barrier()
; #define lane lane_id()
; template <class Epi, class Sched>
; __device__ __forceinline__ void gemm_phase(LAS unsigned char* lds, const Gemm g, const Sched& S, const Epi& E, int wave_id) {
;     ...
;     const int wid = wave_id, lane = tid & 63, wr = wid >> 2, wc = wid & 3, fr = lane & 15, fq = lane >> 4;
;     const int K = g.K, nt = K / BK;
;     unsigned voffA[2], voffB[2];
; #pragma unroll
;     for (int i = 0; i < 2; ++i) { int R, C; stage_rc(tid * 16 + i * 8192, R, C); const int Rb = (R & ~31) + perm32(R & 31);
;         voffA[i] = (unsigned)(R * g.lda + C) * 2u; voffB[i] = (unsigned)(Rb * g.ldb + C) * 2u; }
;     const size_t kstep = (size_t)(BK * 2);
;     const size_t hstepA = (size_t)HALF * g.lda * 2, hstepB = (size_t)HALF * g.ldb * 2;
;     const size_t tstepA = 2 * hstepA, tstepB = 2 * hstepB;
;     const unsigned ldsw = (unsigned)wid * 1024u;
;     const int aoff = lds_byte(wr * 64 + fr, fq * 8), boff = lds_byte(wc * 32 + fr, fq * 8);
;     ...
;     PG8_STAGE(PG8_SB(0, 0), cB, voffB); PG8_STAGE(PG8_SB(0, 1), cB + hstepB, voffB); PG8_STAGE(PG8_SA(0, 0), cA, voffA); PG8_STAGE(PG8_SA(0, 1), cA + hstepA, voffA);
;     if (wr == 1) PG8_BAR;
;     PG8_WAIT_V(2); PG8_BAR;
;     PG8_STAGE(PG8_SB(1, 0), cB + kstep, voffB); PG8_STAGE(PG8_SA(1, 0), cA + kstep, voffA); PG8_STAGE(PG8_SB(1, 1), cB + hstepB + kstep, voffB);
;     PG8_WAIT_V(6); PG8_BAR;
.LBB0_717:
	s_mov_b64 s[6:7], 0x80
	v_readlane_b32 s12, v255, 1
	s_add_i32 m0, s29, 0x18000
	v_lshl_add_u64 v[6:7], v[6:7], 0, s[6:7]
	s_ashr_i32 s49, s12, 31
	global_load_lds_dwordx4 v[6:7], off
	v_lshl_add_u64 v[4:5], v[4:5], 0, s[6:7]
	s_add_i32 m0, s29, 0x1a000
	s_add_i32 s50, s29, 0x8000
	s_add_i32 s51, s29, 0xa000
	global_load_lds_dwordx4 v[4:5], off
	v_lshl_add_u64 v[0:1], v[0:1], 0, s[6:7]
	s_mov_b32 m0, s50
	s_add_u32 s10, s34, 0x40080
	global_load_lds_dwordx4 v[0:1], off
	v_lshl_add_u64 v[0:1], v[2:3], 0, s[6:7]
	s_mov_b32 m0, s51
	s_addc_u32 s11, s35, 0
	global_load_lds_dwordx4 v[0:1], off
	s_add_i32 m0, s29, 0x1c000
	v_lshl_add_u64 v[0:1], s[10:11], 0, v[130:131]
	global_load_lds_dwordx4 v[0:1], off
	v_lshl_add_u64 v[0:1], s[10:11], 0, v[134:135]
	s_add_i32 m0, s29, 0x1e000
	s_sext_i32_i8 s58, s8
	global_load_lds_dwordx4 v[0:1], off
	s_waitcnt vmcnt(8)
	s_barrier
	v_and_b32_e32 v0, 15, v8
	v_lshrrev_b32_e32 v1, 1, v8
	v_or_b32_e32 v158, s55, v0
	v_and_b32_e32 v1, 24, v1
	v_lshlrev_b32_e32 v2, 6, v158
	v_lshlrev_b32_e32 v3, 1, v1
	s_movk_i32 s8, 0x3c0
	v_and_or_b32 v2, v2, s8, v3
	v_lshl_or_b32 v0, v0, 6, v3
	v_lshlrev_b32_e32 v3, 2, v8
	v_and_b32_e32 v3, 32, v3
	v_bitop3_b32 v159, v0, s52, v3 bitop3:0xde
	v_lshlrev_b32_e32 v0, 14, v9
	v_and_b32_e32 v0, 0xffff8000, v0
	v_or_b32_e32 v160, s53, v1
	v_lshl_add_u32 v0, v10, 11, v0
	v_and_b32_e32 v1, 1, v9
	s_cmpk_lt_u32 s80, 0x100
	v_lshl_or_b32 v0, v1, 6, v0
	s_cselect_b64 s[8:9], -1, 0
	s_add_u32 s10, s92, 0x1f400000
	v_lshl_add_u32 v136, v11, 1, v0
	v_lshlrev_b32_e32 v0, 14, v12
	v_lshlrev_b32_e32 v4, 2, v158
	s_addc_u32 s11, s93, 0
	v_and_b32_e32 v0, 0xffff8000, v0
	v_readlane_b32 s13, v255, 2
	v_and_b32_e32 v4, 32, v4
	s_mov_b32 s52, s12
	s_waitcnt vmcnt(6)
	s_add_u32 s12, s92, 0xb400000
	v_lshl_add_u32 v0, v13, 11, v0
	v_and_b32_e32 v1, 1, v12
	v_bitop3_b32 v2, v2, s54, v4 bitop3:0xde
	s_addc_u32 s13, s93, 0
	v_lshl_or_b32 v0, v1, 6, v0
	s_add_i32 s53, 0, 0x10000
	s_add_i32 s54, 0, 0x14000
	v_mov_b32_e32 v137, v131
	v_lshl_add_u32 v138, v14, 1, v0
	v_mov_b32_e32 v139, v131
	v_add_u32_e32 v161, s53, v159
	v_add_u32_e32 v162, s54, v159
	v_add_u32_e32 v163, 0, v2
	s_mov_b32 s14, 0x437f0000
	s_mov_b32 s55, 0xb400000
	v_mov_b64_e32 v[140:141], 0x3ff
	s_barrier
	s_branch .LBB0_720

;     __device__ bool next(int i, Unit& u) const { if (r0 + i >= r1) return false; return base.next(r0 + i, u); }
;     __device__ bool next(int i, Unit& u) const { const int L = i * G + c; if (L >= 256) return false; u.pm = L; u.pn = L >> 3; return true; }
; #define PG8_STAGE(bufoff, gbase, voff) do { _Pragma("unroll") for (int _i = 0; _i < 2; ++_i) \
;         __builtin_amdgcn_global_load_lds((const unsigned*)((const char*)(gbase) + (voff)[_i]), (LAS unsigned*)(lds + (bufoff) + ldsw + _i * 8192), 16, 0, 0); } while (0)
; #define PG8_WAIT_V(n) asm volatile("s_waitcnt vmcnt(" #n ")" ::: "memory")
; #define PG8_BAR __builtin_amdgcn_s_barrier()
;     __device__ bool next(int i, Unit& u) const {
;         const long L = (long)i * G + c; if (L >= nwg) return false;
;         int wgid = (int)L; { const int q = nwg / NXCD, r = nwg % NXCD, xcd = wgid % NXCD, off = wgid / NXCD; wgid = (xcd < r ? xcd * (q + 1) : r * (q + 1) + (xcd - r) * q) + off; }
;         const int nig = WGM * nN, gid = wgid / nig, fm = gid * WGM, gsz = (nM - fm) < WGM ? (nM - fm) : WGM;
;         u.pm = fm + ((wgid % nig) % gsz); u.pn = (wgid % nig) / gsz; return true;
; template <class Epi, class Sched>
; __device__ __forceinline__ void gemm_phase(LAS unsigned char* lds, const Gemm g, const Sched& S, const Epi& E, int wave_id) {
;     ...
;     PG8_STAGE(PG8_SB(0, 0), cB, voffB); PG8_STAGE(PG8_SB(0, 1), cB + hstepB, voffB); PG8_STAGE(PG8_SA(0, 0), cA, voffA); PG8_STAGE(PG8_SA(0, 1), cA + hstepA, voffA);
;     if (wr == 1) PG8_BAR;
;     PG8_WAIT_V(2); PG8_BAR;
;     PG8_STAGE(PG8_SB(1, 0), cB + kstep, voffB); PG8_STAGE(PG8_SA(1, 0), cA + kstep, voffA); PG8_STAGE(PG8_SB(1, 1), cB + hstepB + kstep, voffB);
;     PG8_WAIT_V(6); PG8_BAR;
.LBB0_800:
	v_lshrrev_b32_e32 v16, 1, v14
	v_and_b32_e32 v16, 24, v16
	v_and_b32_e32 v15, 15, v14
	v_lshlrev_b32_e32 v17, 1, v16
	v_lshlrev_b32_e32 v14, 2, v14
	v_lshl_or_b32 v156, s8, 6, v15
	v_lshl_or_b32 v15, v15, 6, v17
	s_lshl_b32 s8, s8, 13
	v_and_b32_e32 v14, 32, v14
	v_bitop3_b32 v17, v15, s8, v14 bitop3:0xde
	s_lshl_b32 s8, s97, 5
	s_and_b32 s16, s8, 0x60
	s_lshl_b32 s8, s16, 7
	v_bitop3_b32 v157, v15, s8, v14 bitop3:0xde
	s_mov_b64 s[8:9], 0x80
	s_add_i32 m0, s27, 0x18000
	v_lshl_add_u64 v[6:7], v[6:7], 0, s[8:9]
	global_load_lds_dwordx4 v[6:7], off
	v_lshl_add_u64 v[4:5], v[4:5], 0, s[8:9]
	s_add_i32 m0, s27, 0x1a000
	s_add_i32 s46, s27, 0x8000
	s_add_i32 s47, s27, 0xa000
	global_load_lds_dwordx4 v[4:5], off
	v_lshl_add_u64 v[0:1], v[0:1], 0, s[8:9]
	s_mov_b32 m0, s46
	s_add_u32 s10, s34, 0x40080
	global_load_lds_dwordx4 v[0:1], off
	v_lshl_add_u64 v[0:1], v[2:3], 0, s[8:9]
	s_mov_b32 m0, s47
	s_addc_u32 s11, s35, 0
	global_load_lds_dwordx4 v[0:1], off
	s_add_i32 m0, s27, 0x1c000
	v_lshl_add_u64 v[0:1], s[10:11], 0, v[130:131]
	global_load_lds_dwordx4 v[0:1], off
	v_lshl_add_u64 v[0:1], s[10:11], 0, v[134:135]
	s_add_i32 m0, s27, 0x1e000
	s_cmpk_lt_u32 s80, 0x100
	global_load_lds_dwordx4 v[0:1], off
	s_waitcnt vmcnt(8)
	s_barrier
	s_cselect_b64 s[10:11], -1, 0
	s_add_u32 s12, s92, 0x1f400000
	s_addc_u32 s13, s93, 0
	s_add_u32 s14, s92, 0xb400000
	s_addc_u32 s15, s93, 0
	s_mul_hi_i32 s17, s4, 3
	s_mul_i32 s4, s4, 3
	s_add_u32 s4, s4, s66
	s_addc_u32 s5, s17, s5
	s_ashr_i32 s17, s4, 31
	s_lshr_b32 s17, s17, 29
	s_add_i32 s17, s4, s17
	s_ashr_i32 s18, s17, 3
	s_and_b32 s17, s17, -8
	s_sub_i32 s17, s4, s17
	s_lshl_b32 s19, s17, 7
	s_cmp_lt_i32 s17, 0
	s_mulk_i32 s17, 0x81
	s_cselect_b32 s17, s17, s19
	s_add_i32 s17, s17, s18
	s_ashr_i32 s18, s17, 31
	s_lshr_b32 s18, s18, 26
	s_add_i32 s18, s17, s18
	s_ashr_i32 s19, s18, 6
	s_lshl_b32 s19, s19, 3
	s_sub_i32 s20, 0x80, s19
	s_min_i32 s20, s20, 8
	s_abs_i32 s22, s20
	v_cvt_f32_u32_e32 v2, s22
	v_mov_b64_e32 v[0:1], 0x400
	v_cmp_lt_i64_e64 s[36:37], s[4:5], v[0:1]
	s_andn2_b32 s18, s18, 63
	v_rcp_iflag_f32_e32 v0, v2
	s_sub_i32 s4, s17, s18
	s_sub_i32 s17, 0, s22
	v_or_b32_e32 v158, s16, v16
	v_mul_f32_e32 v0, 0x4f7ffffe, v0
	v_cvt_u32_f32_e32 v0, v0
	s_abs_i32 s16, s4
	s_xor_b32 s5, s4, s20
	s_ashr_i32 s5, s5, 31
	v_readfirstlane_b32 s18, v0
	s_mul_i32 s17, s17, s18
	s_mul_hi_u32 s17, s18, s17
	s_add_i32 s18, s18, s17
	s_mul_hi_u32 s17, s16, s18
	s_mul_i32 s18, s17, s22
	s_sub_i32 s16, s16, s18
	s_add_i32 s18, s17, 1
	s_sub_i32 s23, s16, s22
	s_cmp_ge_u32 s16, s22
	s_cselect_b32 s17, s18, s17
	v_lshlrev_b32_e32 v0, 14, v8
	s_cselect_b32 s16, s23, s16
	s_add_i32 s18, s17, 1
	v_and_b32_e32 v0, 0xffff8000, v0
	s_cmp_ge_u32 s16, s22
	v_lshl_add_u32 v0, v9, 11, v0
	v_and_b32_e32 v1, 1, v8
	s_cselect_b32 s16, s18, s17
	v_lshl_or_b32 v0, v1, 6, v0
	s_xor_b32 s16, s16, s5
	v_lshl_add_u32 v136, v10, 1, v0
	v_lshlrev_b32_e32 v0, 14, v11
	s_sub_i32 s16, s16, s5
	v_and_b32_e32 v0, 0xffff8000, v0
	s_waitcnt vmcnt(6)
	s_mul_i32 s5, s16, s20
	v_lshl_add_u32 v0, v12, 11, v0
	v_and_b32_e32 v1, 1, v11
	s_sub_i32 s4, s4, s5
	v_lshl_or_b32 v0, v1, 6, v0
	s_add_i32 s48, 0, 0x10000
	s_add_i32 s49, 0, 0x14000
	s_add_i32 s18, s19, s4
	v_mov_b32_e32 v137, v131
	v_lshl_add_u32 v138, v13, 1, v0
	v_mov_b32_e32 v139, v131
	v_add_u32_e32 v159, s48, v157
	v_add_u32_e32 v160, s49, v157
	v_add_u32_e32 v161, 0, v17
	s_mov_b32 s20, 0x437f0000
	s_mov_b32 s50, 0xb400000
	s_barrier
	s_branch .LBB0_803

;     __device__ bool next(int i, Unit& u) const { if (r0 + i >= r1) return false; return base.next(r0 + i, u); }
;     __device__ bool next(int i, Unit& u) const { const int L = i * G + c; if (L >= 256) return false; u.pm = L; u.pn = L >> 3; return true; }
; #define PG8_STAGE(bufoff, gbase, voff) do { _Pragma("unroll") for (int _i = 0; _i < 2; ++_i) \
;         __builtin_amdgcn_global_load_lds((const unsigned*)((const char*)(gbase) + (voff)[_i]), (LAS unsigned*)(lds + (bufoff) + ldsw + _i * 8192), 16, 0, 0); } while (0)
; #define PG8_WAIT_V(n) asm volatile("s_waitcnt vmcnt(" #n ")" ::: "memory")
; #define PG8_BAR __builtin_amdgcn_s_barrier()
;     __device__ bool next(int i, Unit& u) const {
;         const long L = (long)i * G + c; if (L >= nwg) return false;
;         int wgid = (int)L; { const int q = nwg / NXCD, r = nwg % NXCD, xcd = wgid % NXCD, off = wgid / NXCD; wgid = (xcd < r ? xcd * (q + 1) : r * (q + 1) + (xcd - r) * q) + off; }
;         const int nig = WGM * nN, gid = wgid / nig, fm = gid * WGM, gsz = (nM - fm) < WGM ? (nM - fm) : WGM;
;         u.pm = fm + ((wgid % nig) % gsz); u.pn = (wgid % nig) / gsz; return true;
; template <class Epi, class Sched>
; __device__ __forceinline__ void gemm_phase(LAS unsigned char* lds, const Gemm g, const Sched& S, const Epi& E, int wave_id) {
;     ...
;     PG8_STAGE(PG8_SB(0, 0), cB, voffB); PG8_STAGE(PG8_SB(0, 1), cB + hstepB, voffB); PG8_STAGE(PG8_SA(0, 0), cA, voffA); PG8_STAGE(PG8_SA(0, 1), cA + hstepA, voffA);
;     if (wr == 1) PG8_BAR;
;     PG8_WAIT_V(2); PG8_BAR;
;     PG8_STAGE(PG8_SB(1, 0), cB + kstep, voffB); PG8_STAGE(PG8_SA(1, 0), cA + kstep, voffA); PG8_STAGE(PG8_SB(1, 1), cB + hstepB + kstep, voffB);
;     PG8_WAIT_V(6); PG8_BAR;
.LBB0_859:
	v_lshrrev_b32_e32 v16, 1, v14
	v_and_b32_e32 v16, 24, v16
	v_and_b32_e32 v15, 15, v14
	v_lshlrev_b32_e32 v17, 1, v16
	v_lshlrev_b32_e32 v14, 2, v14
	v_lshl_or_b32 v156, s8, 6, v15
	v_lshl_or_b32 v15, v15, 6, v17
	s_lshl_b32 s8, s8, 13
	v_and_b32_e32 v14, 32, v14
	v_bitop3_b32 v17, v15, s8, v14 bitop3:0xde
	s_lshl_b32 s8, s97, 5
	s_and_b32 s16, s8, 0x60
	s_lshl_b32 s8, s16, 7
	v_bitop3_b32 v157, v15, s8, v14 bitop3:0xde
	s_mov_b64 s[8:9], 0x80
	s_add_i32 m0, s27, 0x18000
	v_lshl_add_u64 v[6:7], v[6:7], 0, s[8:9]
	global_load_lds_dwordx4 v[6:7], off
	v_lshl_add_u64 v[4:5], v[4:5], 0, s[8:9]
	s_add_i32 m0, s27, 0x1a000
	s_add_i32 s41, s27, 0x8000
	s_add_i32 s42, s27, 0xa000
	global_load_lds_dwordx4 v[4:5], off
	v_lshl_add_u64 v[0:1], v[0:1], 0, s[8:9]
	s_mov_b32 m0, s41
	s_add_u32 s10, s34, 0x40080
	global_load_lds_dwordx4 v[0:1], off
	v_lshl_add_u64 v[0:1], v[2:3], 0, s[8:9]
	s_mov_b32 m0, s42
	s_addc_u32 s11, s35, 0
	global_load_lds_dwordx4 v[0:1], off
	s_add_i32 m0, s27, 0x1c000
	v_lshl_add_u64 v[0:1], s[10:11], 0, v[130:131]
	global_load_lds_dwordx4 v[0:1], off
	v_lshl_add_u64 v[0:1], s[10:11], 0, v[134:135]
	s_add_i32 m0, s27, 0x1e000
	s_cmpk_lt_u32 s80, 0x100
	global_load_lds_dwordx4 v[0:1], off
	s_waitcnt vmcnt(8)
	s_barrier
	s_cselect_b64 s[10:11], -1, 0
	s_add_u32 s12, s92, 0x1f400000
	s_addc_u32 s13, s93, 0
	s_add_u32 s14, s92, 0xb400000
	s_addc_u32 s15, s93, 0
	s_mul_hi_i32 s17, s4, 3
	s_mul_i32 s4, s4, 3
	s_add_u32 s4, s4, s66
	s_addc_u32 s5, s17, s5
	s_ashr_i32 s17, s4, 31
	s_lshr_b32 s17, s17, 29
	s_add_i32 s17, s4, s17
	s_ashr_i32 s18, s17, 3
	s_and_b32 s17, s17, -8
	s_sub_i32 s17, s4, s17
	s_lshl_b32 s19, s17, 7
	s_cmp_lt_i32 s17, 0
	s_mulk_i32 s17, 0x81
	s_cselect_b32 s17, s17, s19
	s_add_i32 s17, s17, s18
	s_ashr_i32 s18, s17, 31
	s_lshr_b32 s18, s18, 26
	s_add_i32 s18, s17, s18
	s_ashr_i32 s19, s18, 6
	s_lshl_b32 s19, s19, 3
	s_sub_i32 s20, 0x80, s19
	s_min_i32 s20, s20, 8
	s_abs_i32 s22, s20
	v_cvt_f32_u32_e32 v2, s22
	v_mov_b64_e32 v[0:1], 0x400
	v_cmp_lt_i64_e64 s[36:37], s[4:5], v[0:1]
	s_andn2_b32 s18, s18, 63
	v_rcp_iflag_f32_e32 v0, v2
	s_sub_i32 s4, s17, s18
	s_sub_i32 s17, 0, s22
	v_or_b32_e32 v158, s16, v16
	v_mul_f32_e32 v0, 0x4f7ffffe, v0
	v_cvt_u32_f32_e32 v0, v0
	s_abs_i32 s16, s4
	s_xor_b32 s5, s4, s20
	s_ashr_i32 s5, s5, 31
	v_readfirstlane_b32 s18, v0
	s_mul_i32 s17, s17, s18
	s_mul_hi_u32 s17, s18, s17
	s_add_i32 s18, s18, s17
	s_mul_hi_u32 s17, s16, s18
	s_mul_i32 s18, s17, s22
	s_sub_i32 s16, s16, s18
	s_add_i32 s18, s17, 1
	s_sub_i32 s23, s16, s22
	s_cmp_ge_u32 s16, s22
	s_cselect_b32 s17, s18, s17
	v_lshlrev_b32_e32 v0, 14, v8
	s_cselect_b32 s16, s23, s16
	s_add_i32 s18, s17, 1
	v_and_b32_e32 v0, 0xffff8000, v0
	s_cmp_ge_u32 s16, s22
	v_lshl_add_u32 v0, v9, 11, v0
	v_and_b32_e32 v1, 1, v8
	s_cselect_b32 s16, s18, s17
	v_lshl_or_b32 v0, v1, 6, v0
	s_xor_b32 s16, s16, s5
	v_lshl_add_u32 v136, v10, 1, v0
	v_lshlrev_b32_e32 v0, 14, v11
	s_sub_i32 s16, s16, s5
	v_and_b32_e32 v0, 0xffff8000, v0
	s_waitcnt vmcnt(6)
	s_mul_i32 s5, s16, s20
	v_lshl_add_u32 v0, v12, 11, v0
	v_and_b32_e32 v1, 1, v11
	s_sub_i32 s4, s4, s5
	v_lshl_or_b32 v0, v1, 6, v0
	s_add_i32 s43, 0, 0x10000
	s_add_i32 s44, 0, 0x14000
	s_add_i32 s18, s19, s4
	v_mov_b32_e32 v137, v131
	v_lshl_add_u32 v138, v13, 1, v0
	v_mov_b32_e32 v139, v131
	v_add_u32_e32 v159, s43, v157
	v_add_u32_e32 v160, s44, v157
	v_add_u32_e32 v161, 0, v17
	s_mov_b32 s20, 0x437f0000
	s_mov_b32 s45, 0xb400000
	s_barrier
	s_branch .LBB0_862

; #define PG8_STAGE(bufoff, gbase, voff) do { _Pragma("unroll") for (int _i = 0; _i < 2; ++_i) \
;         __builtin_amdgcn_global_load_lds((const unsigned*)((const char*)(gbase) + (voff)[_i]), (LAS unsigned*)(lds + (bufoff) + ldsw + _i * 8192), 16, 0, 0); } while (0)
; #define PG8_WAIT_V(n) asm volatile("s_waitcnt vmcnt(" #n ")" ::: "memory")
; #define PG8_BAR __builtin_amdgcn_s_barrier()
; #define lane lane_id()
; template <class Epi, class Sched>
; __device__ __forceinline__ void gemm_phase(LAS unsigned char* lds, const Gemm g, const Sched& S, const Epi& E, int wave_id) {
;     ...
;     const int wid = wave_id, lane = tid & 63, wr = wid >> 2, wc = wid & 3, fr = lane & 15, fq = lane >> 4;
;     const int K = g.K, nt = K / BK;
;     unsigned voffA[2], voffB[2];
; #pragma unroll
;     for (int i = 0; i < 2; ++i) { int R, C; stage_rc(tid * 16 + i * 8192, R, C); const int Rb = (R & ~31) + perm32(R & 31);
;         voffA[i] = (unsigned)(R * g.lda + C) * 2u; voffB[i] = (unsigned)(Rb * g.ldb + C) * 2u; }
;     const size_t kstep = (size_t)(BK * 2);
;     const size_t hstepA = (size_t)HALF * g.lda * 2, hstepB = (size_t)HALF * g.ldb * 2;
;     const size_t tstepA = 2 * hstepA, tstepB = 2 * hstepB;
;     const unsigned ldsw = (unsigned)wid * 1024u;
;     const int aoff = lds_byte(wr * 64 + fr, fq * 8), boff = lds_byte(wc * 32 + fr, fq * 8);
;     ...
;     PG8_STAGE(PG8_SB(0, 0), cB, voffB); PG8_STAGE(PG8_SB(0, 1), cB + hstepB, voffB); PG8_STAGE(PG8_SA(0, 0), cA, voffA); PG8_STAGE(PG8_SA(0, 1), cA + hstepA, voffA);
;     if (wr == 1) PG8_BAR;
;     PG8_WAIT_V(2); PG8_BAR;
;     PG8_STAGE(PG8_SB(1, 0), cB + kstep, voffB); PG8_STAGE(PG8_SA(1, 0), cA + kstep, voffA); PG8_STAGE(PG8_SB(1, 1), cB + hstepB + kstep, voffB);
;     PG8_WAIT_V(6); PG8_BAR;
.LBB0_930:
	s_lshl_b32 s4, s97, 5
	s_mov_b64 s[12:13], 0x80
	s_and_b32 s6, s4, 0x60
	s_add_i32 m0, s38, 0x18000
	v_lshl_add_u64 v[6:7], v[6:7], 0, s[12:13]
	s_lshl_b32 s7, s6, 7
	global_load_lds_dwordx4 v[6:7], off
	v_lshl_add_u64 v[4:5], v[4:5], 0, s[12:13]
	s_add_i32 m0, s38, 0x1a000
	s_add_i32 s43, s38, 0x8000
	s_add_i32 s44, s38, 0xa000
	global_load_lds_dwordx4 v[4:5], off
	v_lshl_add_u64 v[0:1], v[0:1], 0, s[12:13]
	s_mov_b32 m0, s43
	s_add_u32 s4, s34, 0x18080
	global_load_lds_dwordx4 v[0:1], off
	v_lshl_add_u64 v[0:1], v[2:3], 0, s[12:13]
	s_mov_b32 m0, s44
	s_addc_u32 s5, s35, 0
	global_load_lds_dwordx4 v[0:1], off
	s_add_i32 m0, s38, 0x1c000
	v_lshl_add_u64 v[0:1], s[4:5], 0, v[132:133]
	global_load_lds_dwordx4 v[0:1], off
	v_lshl_add_u64 v[0:1], s[4:5], 0, v[128:129]
	s_add_i32 m0, s38, 0x1e000
	s_cmpk_lt_u32 s80, 0x100
	global_load_lds_dwordx4 v[0:1], off
	s_waitcnt vmcnt(8)
	s_barrier
	v_and_b32_e32 v1, 15, v8
	v_lshrrev_b32_e32 v0, 1, v8
	v_and_b32_e32 v2, 24, v0
	v_lshlrev_b32_e32 v3, 6, v1
	v_lshl_or_b32 v3, v2, 1, v3
	s_cselect_b64 s[4:5], -1, 0
	v_or_b32_e32 v2, s6, v2
	s_lshl_b32 s6, s3, 10
	v_lshlrev_b32_e32 v4, 2, v8
	s_add_u32 s14, s92, 0x1c400000
	v_readlane_b32 s18, v255, 1
	v_and_b32_e32 v4, 32, v4
	s_addc_u32 s15, s93, 0
	s_add_i32 s45, s66, s18
	v_bitop3_b32 v5, v3, s33, v4 bitop3:0xde
	v_bitop3_b32 v3, v3, s7, v4 bitop3:0xde
	v_lshrrev_b32_e32 v2, 4, v2
	v_lshlrev_b32_e32 v1, 4, v1
	s_mul_i32 s7, s45, 0x30000
	v_or3_b32 v139, v1, s6, v2
	s_mul_hi_i32 s6, s45, 0x30000
	s_add_u32 s7, s92, s7
	s_addc_u32 s6, s93, s6
	s_add_u32 s16, s7, 0x17400000
	s_waitcnt vmcnt(6)
	s_addc_u32 s17, s6, 0
	s_add_i32 s50, 0, 0x10000
	s_add_i32 s52, 0, 0x14000
	s_add_i32 s54, 0, 0x18000
	s_add_i32 s58, 0, 0x1c000
	v_and_b32_e32 v0, 8, v0
	v_readlane_b32 s19, v255, 2
	v_add_u32_e32 v147, s50, v3
	v_add_u32_e32 v148, s52, v3
	v_cndmask_b32_e64 v1, 0, 1, s[4:5]
	s_add_i32 s50, s50, s2
	s_add_i32 s52, s52, s2
	v_add_u32_e32 v149, s54, v3
	v_add_u32_e32 v150, s58, v3
	s_add_i32 s54, s54, s2
	s_add_i32 s58, s58, s2
	v_add_u32_e32 v138, 0, v5
	v_or_b32_e32 v151, 0x100, v139
	v_or_b32_e32 v254, 0x200, v139
	v_or_b32_e32 v142, 0x300, v139
	v_add_u32_e32 v143, 0x800, v139
	v_add_u32_e32 v144, 0x900, v139
	v_add_u32_e32 v145, 0xa00, v139
	v_add_u32_e32 v146, 0xb00, v139
	s_mul_hi_i32 s46, s18, 0x30000
	s_mul_i32 s47, s18, 0x30000
	s_add_i32 s48, s38, 0xc000
	s_add_i32 s49, s38, 0xe000
	s_mov_b64 s[18:19], 0x100
	s_mov_b64 s[20:21], 0x180
	s_mov_b64 s[22:23], 0x200
	s_mov_b64 s[24:25], 0x280
	v_lshlrev_b32_e32 v136, 1, v0
	s_add_i32 s51, s50, 0x2000
	s_add_i32 s53, s52, 0x2000
	s_add_i32 s55, s54, 0x2000
	s_add_i32 s59, s58, 0x2000
	v_cmp_ne_u32_e64 s[4:5], 1, v1
	s_mov_b32 s62, s66
	s_mov_b64 s[26:27], s[30:31]
	s_barrier
	s_waitcnt vmcnt(0)
	s_branch .LBB0_933

; #define PG8_STAGE(bufoff, gbase, voff) do { _Pragma("unroll") for (int _i = 0; _i < 2; ++_i) \
;         __builtin_amdgcn_global_load_lds((const unsigned*)((const char*)(gbase) + (voff)[_i]), (LAS unsigned*)(lds + (bufoff) + ldsw + _i * 8192), 16, 0, 0); } while (0)
; #define PG8_WAIT_V(n) asm volatile("s_waitcnt vmcnt(" #n ")" ::: "memory")
; #define PG8_BAR __builtin_amdgcn_s_barrier()
; #define lane lane_id()
; template <class Epi, class Sched>
; __device__ __forceinline__ void gemm_phase(LAS unsigned char* lds, const Gemm g, const Sched& S, const Epi& E, int wave_id) {
;     ...
;     const int wid = wave_id, lane = tid & 63, wr = wid >> 2, wc = wid & 3, fr = lane & 15, fq = lane >> 4;
;     const int K = g.K, nt = K / BK;
;     unsigned voffA[2], voffB[2];
; #pragma unroll
;     for (int i = 0; i < 2; ++i) { int R, C; stage_rc(tid * 16 + i * 8192, R, C); const int Rb = (R & ~31) + perm32(R & 31);
;         voffA[i] = (unsigned)(R * g.lda + C) * 2u; voffB[i] = (unsigned)(Rb * g.ldb + C) * 2u; }
;     const size_t kstep = (size_t)(BK * 2);
;     const size_t hstepA = (size_t)HALF * g.lda * 2, hstepB = (size_t)HALF * g.ldb * 2;
;     const size_t tstepA = 2 * hstepA, tstepB = 2 * hstepB;
;     const unsigned ldsw = (unsigned)wid * 1024u;
;     const int aoff = lds_byte(wr * 64 + fr, fq * 8), boff = lds_byte(wc * 32 + fr, fq * 8);
;     ...
;     PG8_STAGE(PG8_SB(0, 0), cB, voffB); PG8_STAGE(PG8_SB(0, 1), cB + hstepB, voffB); PG8_STAGE(PG8_SA(0, 0), cA, voffA); PG8_STAGE(PG8_SA(0, 1), cA + hstepA, voffA);
;     if (wr == 1) PG8_BAR;
;     PG8_WAIT_V(2); PG8_BAR;
;     PG8_STAGE(PG8_SB(1, 0), cB + kstep, voffB); PG8_STAGE(PG8_SA(1, 0), cA + kstep, voffA); PG8_STAGE(PG8_SB(1, 1), cB + hstepB + kstep, voffB);
;     PG8_WAIT_V(6); PG8_BAR;
.LBB0_950:
	s_add_u32 s42, s92, 0x13400000
	s_mov_b64 s[10:11], 0x80
	s_addc_u32 s43, s93, 0
	s_bfe_u32 s5, s80, 0x20006
	s_add_i32 m0, s37, 0x18000
	v_lshl_add_u64 v[6:7], v[6:7], 0, s[10:11]
	s_lshl_b32 s44, s3, 6
	s_lshl_b32 s14, s5, 12
	global_load_lds_dwordx4 v[6:7], off
	v_lshl_add_u64 v[4:5], v[4:5], 0, s[10:11]
	s_add_i32 m0, s37, 0x1a000
	s_add_i32 s45, s37, 0x8000
	s_add_i32 s46, s37, 0xa000
	global_load_lds_dwordx4 v[4:5], off
	v_lshl_add_u64 v[0:1], v[0:1], 0, s[10:11]
	s_mov_b32 m0, s45
	s_add_u32 s12, s26, 0x40080
	global_load_lds_dwordx4 v[0:1], off
	v_lshl_add_u64 v[0:1], v[2:3], 0, s[10:11]
	s_mov_b32 m0, s46
	s_addc_u32 s13, s27, 0
	global_load_lds_dwordx4 v[0:1], off
	s_add_i32 m0, s37, 0x1c000
	v_lshl_add_u64 v[0:1], s[12:13], 0, v[130:131]
	global_load_lds_dwordx4 v[0:1], off
	v_lshl_add_u64 v[0:1], s[12:13], 0, v[134:135]
	s_add_i32 m0, s37, 0x1e000
	v_and_b32_e32 v2, 15, v8
	global_load_lds_dwordx4 v[0:1], off
	s_waitcnt vmcnt(8)
	s_barrier
	v_bfe_u32 v1, v8, 4, 2
	v_lshrrev_b32_e32 v0, 4, v8
	v_lshlrev_b32_e32 v1, 4, v1
	v_lshlrev_b32_e32 v4, 2, v8
	v_lshl_or_b32 v3, v2, 6, v1
	v_and_b32_e32 v4, 32, v4
	v_bfe_u32 v0, v0, 1, 1
	v_bitop3_b32 v5, v3, s33, v4 bitop3:0xde
	v_bitop3_b32 v150, v3, s14, v4 bitop3:0xde
	v_lshl_or_b32 v0, s5, 1, v0
	v_and_or_b32 v3, v1, 16, v2
	v_lshlrev_b32_e32 v136, 4, v3
	v_mul_u32_u24_e32 v3, 0x210, v0
	v_lshlrev_b32_e32 v138, 11, v0
	v_lshlrev_b32_e32 v0, 14, v9
	v_and_b32_e32 v0, 0xffff8000, v0
	s_cmpk_lt_u32 s80, 0x100
	s_mul_i32 s14, s3, 0x2100
	v_lshl_add_u32 v0, v10, 11, v0
	v_and_b32_e32 v6, 1, v9
	s_cselect_b64 s[12:13], -1, 0
	s_add_i32 s14, s14, 0
	v_lshl_or_b32 v0, v6, 6, v0
	s_lshl_b32 s5, s5, 6
	s_add_i32 s14, s14, 0x20000
	v_lshl_add_u32 v142, v11, 1, v0
	v_lshlrev_b32_e32 v0, 14, v12
	s_add_i32 s5, s5, s14
	v_and_b32_e32 v0, 0xffff8000, v0
	s_sext_i32_i8 s23, s4
	s_waitcnt vmcnt(6)
	s_movk_i32 s4, 0x210
	v_mov_b32_e32 v4, s5
	v_lshl_add_u32 v0, v13, 11, v0
	v_and_b32_e32 v6, 1, v12
	v_readlane_b32 s16, v255, 1
	v_mad_u32_u24 v2, v2, s4, v4
	v_add_u32_e32 v4, s14, v136
	v_lshl_or_b32 v0, v6, 6, v0
	s_add_i32 s47, 0, 0x10000
	s_add_i32 s48, 0, 0x14000
	v_mov_b32_e32 v137, v131
	s_ashr_i32 s3, s16, 31
	s_mov_b32 s33, s16
	v_mov_b32_e32 v139, v131
	v_or_b32_e32 v140, 0x4000, v138
	v_mov_b32_e32 v141, v131
	v_mov_b32_e32 v143, v131
	v_lshl_add_u32 v144, v14, 1, v0
	v_mov_b32_e32 v145, v131
	v_mov_b64_e32 v[146:147], 0x200
	v_mov_b64_e32 v[148:149], 0x1ff
	v_add_u32_e32 v151, s47, v150
	v_add_u32_e32 v152, s48, v150
	v_add_u32_e32 v153, 0, v5
	v_add_u32_e32 v154, v2, v1
	v_add_u32_e32 v155, v4, v3
	s_barrier
	v_readlane_b32 s17, v255, 2
	s_waitcnt vmcnt(0)
	s_branch .LBB0_953

; #define PG8_STAGE(bufoff, gbase, voff) do { _Pragma("unroll") for (int _i = 0; _i < 2; ++_i) \
;         __builtin_amdgcn_global_load_lds((const unsigned*)((const char*)(gbase) + (voff)[_i]), (LAS unsigned*)(lds + (bufoff) + ldsw + _i * 8192), 16, 0, 0); } while (0)
; #define PG8_WAIT_V(n) asm volatile("s_waitcnt vmcnt(" #n ")" ::: "memory")
; #define PG8_BAR __builtin_amdgcn_s_barrier()
; #define lane lane_id()
; template <class Epi, class Sched>
; __device__ __forceinline__ void gemm_phase(LAS unsigned char* lds, const Gemm g, const Sched& S, const Epi& E, int wave_id) {
;     ...
;     const int wid = wave_id, lane = tid & 63, wr = wid >> 2, wc = wid & 3, fr = lane & 15, fq = lane >> 4;
;     const int K = g.K, nt = K / BK;
;     unsigned voffA[2], voffB[2];
; #pragma unroll
;     for (int i = 0; i < 2; ++i) { int R, C; stage_rc(tid * 16 + i * 8192, R, C); const int Rb = (R & ~31) + perm32(R & 31);
;         voffA[i] = (unsigned)(R * g.lda + C) * 2u; voffB[i] = (unsigned)(Rb * g.ldb + C) * 2u; }
;     const size_t kstep = (size_t)(BK * 2);
;     const size_t hstepA = (size_t)HALF * g.lda * 2, hstepB = (size_t)HALF * g.ldb * 2;
;     const size_t tstepA = 2 * hstepA, tstepB = 2 * hstepB;
;     const unsigned ldsw = (unsigned)wid * 1024u;
;     const int aoff = lds_byte(wr * 64 + fr, fq * 8), boff = lds_byte(wc * 32 + fr, fq * 8);
;     ...
;     PG8_STAGE(PG8_SB(0, 0), cB, voffB); PG8_STAGE(PG8_SB(0, 1), cB + hstepB, voffB); PG8_STAGE(PG8_SA(0, 0), cA, voffA); PG8_STAGE(PG8_SA(0, 1), cA + hstepA, voffA);
;     if (wr == 1) PG8_BAR;
;     PG8_WAIT_V(2); PG8_BAR;
;     PG8_STAGE(PG8_SB(1, 0), cB + kstep, voffB); PG8_STAGE(PG8_SA(1, 0), cA + kstep, voffA); PG8_STAGE(PG8_SB(1, 1), cB + hstepB + kstep, voffB);
;     PG8_WAIT_V(6); PG8_BAR;
.LBB0_1031:
	s_lshl_b32 s10, s97, 5
	s_and_b32 s15, s10, 0x60
	s_mov_b64 s[10:11], 0x80
	s_add_i32 m0, s25, 0x18000
	v_lshl_add_u64 v[6:7], v[6:7], 0, s[10:11]
	s_lshl_b32 s14, s5, 13
	s_lshl_b32 s16, s15, 7
	global_load_lds_dwordx4 v[6:7], off
	v_lshl_add_u64 v[4:5], v[4:5], 0, s[10:11]
	s_add_i32 m0, s25, 0x1a000
	s_add_i32 s41, s25, 0x8000
	s_add_i32 s42, s25, 0xa000
	global_load_lds_dwordx4 v[4:5], off
	v_lshl_add_u64 v[0:1], v[0:1], 0, s[10:11]
	s_mov_b32 m0, s41
	s_add_u32 s12, s28, 0x20080
	global_load_lds_dwordx4 v[0:1], off
	v_lshl_add_u64 v[0:1], v[2:3], 0, s[10:11]
	s_mov_b32 m0, s42
	s_addc_u32 s13, s29, 0
	global_load_lds_dwordx4 v[0:1], off
	s_add_i32 m0, s25, 0x1c000
	v_lshl_add_u64 v[0:1], s[12:13], 0, v[170:171]
	global_load_lds_dwordx4 v[0:1], off
	v_lshl_add_u64 v[0:1], s[12:13], 0, v[174:175]
	s_add_i32 m0, s25, 0x1e000
	s_cmpk_lt_u32 s80, 0x100
	global_load_lds_dwordx4 v[0:1], off
	s_waitcnt vmcnt(8)
	s_barrier
	v_lshrrev_b32_e32 v0, 1, v8
	v_and_b32_e32 v2, 24, v0
	s_sext_i32_i8 s47, s4
	v_and_b32_e32 v1, 15, v8
	v_lshlrev_b32_e32 v0, 1, v2
	v_lshlrev_b32_e32 v3, 2, v8
	s_cselect_b64 s[12:13], -1, 0
	s_lshl_b32 s4, s15, 1
	v_lshl_or_b32 v198, s5, 6, v1
	v_lshl_or_b32 v1, v1, 6, v0
	v_and_b32_e32 v3, 32, v3
	s_add_u32 s4, s92, s4
	v_bitop3_b32 v4, v1, s14, v3 bitop3:0xde
	v_bitop3_b32 v199, v1, s16, v3 bitop3:0xde
	s_addc_u32 s5, s93, 0
	v_mov_b32_e32 v1, v171
	v_lshl_add_u64 v[0:1], s[4:5], 0, v[0:1]
	s_mov_b64 s[4:5], 0x1a400000
	v_lshl_add_u64 v[176:177], v[0:1], 0, s[4:5]
	v_lshlrev_b32_e32 v0, 13, v9
	v_and_b32_e32 v0, 0xffffc000, v0
	v_lshl_add_u32 v0, v10, 10, v0
	v_and_b32_e32 v1, 1, v9
	v_lshl_or_b32 v0, v1, 6, v0
	v_lshl_add_u32 v178, v11, 1, v0
	v_lshlrev_b32_e32 v0, 13, v12
	v_and_b32_e32 v0, 0xffffc000, v0
	s_waitcnt vmcnt(6)
	s_add_u32 s14, s92, 0xf400000
	v_lshl_add_u32 v0, v13, 10, v0
	v_and_b32_e32 v1, 1, v12
	v_or_b32_e32 v200, s15, v2
	s_addc_u32 s15, s93, 0
	v_readlane_b32 s4, v255, 1
	v_lshl_or_b32 v0, v1, 6, v0
	s_add_i32 s45, 0, 0x10000
	s_add_i32 s46, 0, 0x14000
	s_ashr_i32 s43, s4, 31
	s_mov_b32 s44, s4
	v_mov_b32_e32 v179, v171
	v_lshl_add_u32 v180, v14, 1, v0
	v_mov_b32_e32 v181, v171
	v_mov_b64_e32 v[182:183], 0x200
	v_mov_b64_e32 v[184:185], 0x1ff
	v_add_u32_e32 v201, s45, v199
	v_add_u32_e32 v202, s46, v199
	v_add_u32_e32 v203, 0, v4
	s_barrier
	v_readlane_b32 s5, v255, 2
	s_branch .LBB0_1034

; #define PG8_STAGE(bufoff, gbase, voff) do { _Pragma("unroll") for (int _i = 0; _i < 2; ++_i) \
;         __builtin_amdgcn_global_load_lds((const unsigned*)((const char*)(gbase) + (voff)[_i]), (LAS unsigned*)(lds + (bufoff) + ldsw + _i * 8192), 16, 0, 0); } while (0)
; #define PG8_WAIT_V(n) asm volatile("s_waitcnt vmcnt(" #n ")" ::: "memory")
; #define PG8_BAR __builtin_amdgcn_s_barrier()
; #define lane lane_id()
; template <class Epi, class Sched>
; __device__ __forceinline__ void gemm_phase(LAS unsigned char* lds, const Gemm g, const Sched& S, const Epi& E, int wave_id) {
;     ...
;     const int wid = wave_id, lane = tid & 63, wr = wid >> 2, wc = wid & 3, fr = lane & 15, fq = lane >> 4;
;     const int K = g.K, nt = K / BK;
;     unsigned voffA[2], voffB[2];
; #pragma unroll
;     for (int i = 0; i < 2; ++i) { int R, C; stage_rc(tid * 16 + i * 8192, R, C); const int Rb = (R & ~31) + perm32(R & 31);
;         voffA[i] = (unsigned)(R * g.lda + C) * 2u; voffB[i] = (unsigned)(Rb * g.ldb + C) * 2u; }
;     const size_t kstep = (size_t)(BK * 2);
;     const size_t hstepA = (size_t)HALF * g.lda * 2, hstepB = (size_t)HALF * g.ldb * 2;
;     const size_t tstepA = 2 * hstepA, tstepB = 2 * hstepB;
;     const unsigned ldsw = (unsigned)wid * 1024u;
;     const int aoff = lds_byte(wr * 64 + fr, fq * 8), boff = lds_byte(wc * 32 + fr, fq * 8);
;     ...
;     PG8_STAGE(PG8_SB(0, 0), cB, voffB); PG8_STAGE(PG8_SB(0, 1), cB + hstepB, voffB); PG8_STAGE(PG8_SA(0, 0), cA, voffA); PG8_STAGE(PG8_SA(0, 1), cA + hstepA, voffA);
;     if (wr == 1) PG8_BAR;
;     PG8_WAIT_V(2); PG8_BAR;
;     PG8_STAGE(PG8_SB(1, 0), cB + kstep, voffB); PG8_STAGE(PG8_SA(1, 0), cA + kstep, voffA); PG8_STAGE(PG8_SB(1, 1), cB + hstepB + kstep, voffB);
;     PG8_WAIT_V(6); PG8_BAR;
.LBB0_1136:
	s_mov_b64 s[12:13], 0x80
	s_bfe_u32 s16, s80, 0x20006
	s_add_i32 m0, s38, 0x18000
	v_lshl_add_u64 v[6:7], v[6:7], 0, s[12:13]
	s_lshl_b32 s43, s5, 6
	s_lshl_b32 s18, s5, 13
	s_lshl_b32 s19, s16, 5
	s_lshl_b32 s20, s16, 12
	global_load_lds_dwordx4 v[6:7], off
	v_lshl_add_u64 v[4:5], v[4:5], 0, s[12:13]
	s_add_i32 m0, s38, 0x1a000
	s_add_i32 s44, s38, 0x8000
	s_add_i32 s45, s38, 0xa000
	global_load_lds_dwordx4 v[4:5], off
	v_lshl_add_u64 v[0:1], v[0:1], 0, s[12:13]
	s_mov_b32 m0, s44
	s_add_u32 s14, s30, 0x20080
	global_load_lds_dwordx4 v[0:1], off
	v_lshl_add_u64 v[0:1], v[2:3], 0, s[12:13]
	s_mov_b32 m0, s45
	s_addc_u32 s15, s31, 0
	global_load_lds_dwordx4 v[0:1], off
	s_add_i32 m0, s38, 0x1c000
	v_lshl_add_u64 v[0:1], s[14:15], 0, v[154:155]
	global_load_lds_dwordx4 v[0:1], off
	v_lshl_add_u64 v[0:1], s[14:15], 0, v[158:159]
	s_add_i32 m0, s38, 0x1e000
	s_cmpk_lt_u32 s80, 0x100
	global_load_lds_dwordx4 v[0:1], off
	s_waitcnt vmcnt(8)
	s_barrier
	s_sext_i32_i8 s27, s4
	v_bfe_u32 v1, v9, 4, 2
	s_cselect_b64 s[14:15], -1, 0
	s_lshl_b32 s4, s16, 6
	v_and_b32_e32 v204, 15, v9
	v_lshlrev_b32_e32 v2, 4, v1
	v_lshlrev_b32_e32 v4, 2, v9
	s_add_u32 s46, s92, 0xb400000
	v_lshl_or_b32 v3, v204, 6, v2
	v_and_b32_e32 v4, 32, v4
	s_addc_u32 s47, s93, 0
	v_bitop3_b32 v5, v3, s18, v4 bitop3:0xde
	v_bitop3_b32 v205, v3, s20, v4 bitop3:0xde
	s_add_u32 s48, s92, 0x13400000
	v_lshlrev_b32_e32 v4, 13, v8
	s_addc_u32 s49, s93, 0
	v_and_b32_e32 v4, 0xffffc000, v4
	s_mulk_i32 s5, 0x2100
	s_add_u32 s50, s92, 0x7400000
	v_lshl_add_u32 v4, v10, 10, v4
	v_and_b32_e32 v6, 1, v8
	v_lshrrev_b32_e32 v0, 4, v9
	s_addc_u32 s51, s93, 0
	s_add_i32 s5, s5, 0
	v_lshl_or_b32 v4, v6, 6, v4
	v_bfe_u32 v0, v0, 1, 1
	s_add_i32 s5, s5, 0x20000
	v_lshl_add_u32 v170, v11, 1, v4
	v_lshlrev_b32_e32 v4, 13, v12
	v_lshl_or_b32 v162, v1, 3, s19
	v_lshl_or_b32 v0, s16, 1, v0
	v_and_or_b32 v1, v2, 16, v204
	s_add_i32 s4, s4, s5
	v_and_b32_e32 v4, 0xffffc000, v4
	s_waitcnt vmcnt(6)
	v_lshlrev_b32_e32 v164, 4, v1
	s_movk_i32 s16, 0x210
	v_mul_u32_u24_e32 v1, 0x210, v0
	v_lshlrev_b32_e32 v166, 11, v0
	v_mov_b32_e32 v0, s4
	v_lshl_add_u32 v4, v13, 10, v4
	v_and_b32_e32 v6, 1, v12
	v_mad_u32_u24 v0, v204, s16, v0
	v_add_u32_e32 v3, s5, v164
	v_readlane_b32 s4, v255, 1
	v_lshl_or_b32 v4, v6, 6, v4
	s_add_i32 s54, 0, 0x10000
	s_add_i32 s55, 0, 0x14000
	v_mov_b32_e32 v163, v161
	v_mov_b32_e32 v165, v161
	v_mov_b32_e32 v167, v161
	v_or_b32_e32 v168, 0x4000, v166
	v_mov_b32_e32 v169, v161
	s_ashr_i32 s52, s4, 31
	s_mov_b32 s53, s4
	v_mov_b32_e32 v171, v161
	v_lshl_add_u32 v172, v14, 1, v4
	v_mov_b32_e32 v173, v161
	v_mov_b64_e32 v[174:175], 0x200
	v_mov_b64_e32 v[176:177], 0x1ff
	v_add_u32_e32 v206, s54, v205
	v_add_u32_e32 v207, s55, v205
	v_add_u32_e32 v208, 0, v5
	v_lshlrev_b32_e32 v160, 1, v162
	s_mov_b32 s16, 0x3b808081
	v_add_u32_e32 v209, v0, v2
	v_add_u32_e32 v210, v3, v1
	s_barrier
	v_readlane_b32 s5, v255, 2
	s_branch .LBB0_1139

; #define PG8_STAGE(bufoff, gbase, voff) do { _Pragma("unroll") for (int _i = 0; _i < 2; ++_i) \
;         __builtin_amdgcn_global_load_lds((const unsigned*)((const char*)(gbase) + (voff)[_i]), (LAS unsigned*)(lds + (bufoff) + ldsw + _i * 8192), 16, 0, 0); } while (0)
; #define PG8_WAIT_V(n) asm volatile("s_waitcnt vmcnt(" #n ")" ::: "memory")
; #define PG8_BAR __builtin_amdgcn_s_barrier()
; #define lane lane_id()
; template <class Epi, class Sched>
; __device__ __forceinline__ void gemm_phase(LAS unsigned char* lds, const Gemm g, const Sched& S, const Epi& E, int wave_id) {
;     ...
;     const int wid = wave_id, lane = tid & 63, wr = wid >> 2, wc = wid & 3, fr = lane & 15, fq = lane >> 4;
;     const int K = g.K, nt = K / BK;
;     unsigned voffA[2], voffB[2];
; #pragma unroll
;     for (int i = 0; i < 2; ++i) { int R, C; stage_rc(tid * 16 + i * 8192, R, C); const int Rb = (R & ~31) + perm32(R & 31);
;         voffA[i] = (unsigned)(R * g.lda + C) * 2u; voffB[i] = (unsigned)(Rb * g.ldb + C) * 2u; }
;     const size_t kstep = (size_t)(BK * 2);
;     const size_t hstepA = (size_t)HALF * g.lda * 2, hstepB = (size_t)HALF * g.ldb * 2;
;     const size_t tstepA = 2 * hstepA, tstepB = 2 * hstepB;
;     const unsigned ldsw = (unsigned)wid * 1024u;
;     const int aoff = lds_byte(wr * 64 + fr, fq * 8), boff = lds_byte(wc * 32 + fr, fq * 8);
;     ...
;     PG8_STAGE(PG8_SB(0, 0), cB, voffB); PG8_STAGE(PG8_SB(0, 1), cB + hstepB, voffB); PG8_STAGE(PG8_SA(0, 0), cA, voffA); PG8_STAGE(PG8_SA(0, 1), cA + hstepA, voffA);
;     if (wr == 1) PG8_BAR;
;     PG8_WAIT_V(2); PG8_BAR;
;     PG8_STAGE(PG8_SB(1, 0), cB + kstep, voffB); PG8_STAGE(PG8_SA(1, 0), cA + kstep, voffA); PG8_STAGE(PG8_SB(1, 1), cB + hstepB + kstep, voffB);
;     PG8_WAIT_V(6); PG8_BAR;
.LBB0_1241:
	s_mov_b64 s[16:17], 0x80
	s_add_i32 m0, s49, 0x18000
	v_lshl_add_u64 v[6:7], v[6:7], 0, s[16:17]
	global_load_lds_dwordx4 v[6:7], off
	v_lshl_add_u64 v[4:5], v[4:5], 0, s[16:17]
	s_add_i32 m0, s49, 0x1a000
	s_add_i32 s54, s49, 0x8000
	s_add_i32 s55, s49, 0xa000
	global_load_lds_dwordx4 v[4:5], off
	v_lshl_add_u64 v[0:1], v[0:1], 0, s[16:17]
	s_mov_b32 m0, s54
	s_add_u32 s6, s36, 0x40080
	global_load_lds_dwordx4 v[0:1], off
	v_lshl_add_u64 v[0:1], v[2:3], 0, s[16:17]
	s_mov_b32 m0, s55
	s_addc_u32 s7, s37, 0
	global_load_lds_dwordx4 v[0:1], off
	s_add_i32 m0, s49, 0x1c000
	v_lshl_add_u64 v[0:1], s[6:7], 0, v[146:147]
	global_load_lds_dwordx4 v[0:1], off
	v_lshl_add_u64 v[0:1], s[6:7], 0, v[150:151]
	s_add_i32 m0, s49, 0x1e000
	v_and_b32_e32 v176, 15, v8
	global_load_lds_dwordx4 v[0:1], off
	s_waitcnt vmcnt(8)
	s_barrier
	v_bfe_u32 v1, v8, 4, 2
	v_or_b32_e32 v2, s3, v176
	s_sext_i32_i8 s31, s4
	v_lshlrev_b32_e32 v3, 6, v2
	v_lshlrev_b32_e32 v4, 4, v1
	s_movk_i32 s4, 0x3c0
	v_lshlrev_b32_e32 v2, 2, v2
	v_lshrrev_b32_e32 v0, 4, v8
	v_and_or_b32 v3, v3, s4, v4
	v_and_b32_e32 v2, 32, v2
	v_lshlrev_b32_e32 v5, 2, v8
	v_bitop3_b32 v2, v3, s42, v2 bitop3:0xde
	v_lshl_or_b32 v3, v176, 6, v4
	v_and_b32_e32 v5, 32, v5
	s_cmpk_lt_u32 s80, 0x100
	v_bfe_u32 v0, v0, 1, 1
	v_bitop3_b32 v177, v3, s41, v5 bitop3:0xde
	s_cselect_b64 s[18:19], -1, 0
	s_lshl_b32 s20, s33, 6
	v_lshl_or_b32 v0, s33, 1, v0
	v_and_or_b32 v3, v4, 16, v176
	v_readlane_b32 s6, v255, 1
	v_lshlrev_b32_e32 v152, 4, v3
	v_mul_u32_u24_e32 v3, 0x210, v0
	v_lshlrev_b32_e32 v154, 11, v0
	v_cmp_eq_u32_e64 s[4:5], 0, v1
	v_readlane_b32 s7, v255, 2
	s_ashr_i32 s56, s6, 31
	v_or_b32_e32 v0, s20, v4
	v_mov_b32_e32 v1, v147
	v_lshlrev_b32_e32 v5, 14, v9
	s_mov_b32 s57, s6
	v_lshl_add_u64 v[158:159], s[92:93], 0, v[0:1]
	s_mov_b64 s[6:7], 0x3400000
	s_add_u32 s58, s92, 0xb400000
	v_and_b32_e32 v5, 0xffff8000, v5
	v_lshl_add_u64 v[160:161], v[158:159], 0, s[6:7]
	s_addc_u32 s59, s93, 0
	s_add_i32 s6, s40, 0
	v_lshl_add_u32 v5, v10, 11, v5
	v_and_b32_e32 v6, 1, v9
	s_add_i32 s6, s6, 0x20000
	v_lshl_or_b32 v5, v6, 6, v5
	s_add_i32 s7, s20, s6
	v_lshl_add_u32 v162, v11, 1, v5
	v_lshlrev_b32_e32 v5, 14, v12
	s_movk_i32 s21, 0x210
	v_mov_b32_e32 v0, s7
	v_and_b32_e32 v5, 0xffff8000, v5
	s_waitcnt vmcnt(6)
	v_mad_u32_u24 v0, v176, s21, v0
	s_add_u32 s20, s92, 0x1f440000
	v_lshl_add_u32 v5, v13, 11, v5
	v_and_b32_e32 v6, 1, v12
	v_add_u32_e32 v1, s6, v152
	s_addc_u32 s21, s93, 0
	v_lshl_or_b32 v5, v6, 6, v5
	s_add_i32 s60, 0, 0x10000
	s_add_i32 s61, 0, 0x14000
	v_add_u32_e32 v181, v0, v4
	v_mbcnt_lo_u32_b32 v0, -1, 0
	v_mov_b32_e32 v153, v147
	v_mov_b32_e32 v155, v147
	v_or_b32_e32 v156, 0x4000, v154
	v_mov_b32_e32 v157, v147
	v_mov_b32_e32 v163, v147
	v_lshl_add_u32 v164, v14, 1, v5
	v_mov_b32_e32 v165, v147
	v_mov_b64_e32 v[166:167], 0x200
	v_mov_b64_e32 v[168:169], 0x1ff
	v_add_u32_e32 v178, s60, v177
	v_add_u32_e32 v179, s61, v177
	v_add_u32_e32 v180, 0, v2
	s_mov_b32 s62, 0x3400000
	v_add_u32_e32 v182, v1, v3
	v_mbcnt_hi_u32_b32 v183, -1, v0
	s_barrier
	s_branch .LBB0_1244

; #define PG8_STAGE(bufoff, gbase, voff) do { _Pragma("unroll") for (int _i = 0; _i < 2; ++_i) \
;         __builtin_amdgcn_global_load_lds((const unsigned*)((const char*)(gbase) + (voff)[_i]), (LAS unsigned*)(lds + (bufoff) + ldsw + _i * 8192), 16, 0, 0); } while (0)
; #define PG8_WAIT_V(n) asm volatile("s_waitcnt vmcnt(" #n ")" ::: "memory")
; #define PG8_BAR __builtin_amdgcn_s_barrier()
; #define lane lane_id()
; template <class Epi, class Sched>
; __device__ __forceinline__ void gemm_phase(LAS unsigned char* lds, const Gemm g, const Sched& S, const Epi& E, int wave_id) {
;     ...
;     const int wid = wave_id, lane = tid & 63, wr = wid >> 2, wc = wid & 3, fr = lane & 15, fq = lane >> 4;
;     const int K = g.K, nt = K / BK;
;     unsigned voffA[2], voffB[2];
; #pragma unroll
;     for (int i = 0; i < 2; ++i) { int R, C; stage_rc(tid * 16 + i * 8192, R, C); const int Rb = (R & ~31) + perm32(R & 31);
;         voffA[i] = (unsigned)(R * g.lda + C) * 2u; voffB[i] = (unsigned)(Rb * g.ldb + C) * 2u; }
;     const size_t kstep = (size_t)(BK * 2);
;     const size_t hstepA = (size_t)HALF * g.lda * 2, hstepB = (size_t)HALF * g.ldb * 2;
;     const size_t tstepA = 2 * hstepA, tstepB = 2 * hstepB;
;     const unsigned ldsw = (unsigned)wid * 1024u;
;     const int aoff = lds_byte(wr * 64 + fr, fq * 8), boff = lds_byte(wc * 32 + fr, fq * 8);
;     ...
;     PG8_STAGE(PG8_SB(0, 0), cB, voffB); PG8_STAGE(PG8_SB(0, 1), cB + hstepB, voffB); PG8_STAGE(PG8_SA(0, 0), cA, voffA); PG8_STAGE(PG8_SA(0, 1), cA + hstepA, voffA);
;     if (wr == 1) PG8_BAR;
;     PG8_WAIT_V(2); PG8_BAR;
;     PG8_STAGE(PG8_SB(1, 0), cB + kstep, voffB); PG8_STAGE(PG8_SA(1, 0), cA + kstep, voffA); PG8_STAGE(PG8_SB(1, 1), cB + hstepB + kstep, voffB);
;     PG8_WAIT_V(6); PG8_BAR;
.LBB0_1267:
	s_add_u32 s56, s92, 0x13400000
	s_mov_b64 s[12:13], 0x80
	s_addc_u32 s57, s93, 0
	s_add_i32 m0, s51, 0x18000
	v_lshl_add_u64 v[6:7], v[6:7], 0, s[12:13]
	global_load_lds_dwordx4 v[6:7], off
	v_lshl_add_u64 v[4:5], v[4:5], 0, s[12:13]
	s_add_i32 m0, s51, 0x1a000
	s_add_i32 s58, s51, 0x8000
	s_add_i32 s59, s51, 0xa000
	global_load_lds_dwordx4 v[4:5], off
	v_lshl_add_u64 v[0:1], v[0:1], 0, s[12:13]
	s_mov_b32 m0, s58
	s_add_u32 s14, s26, 0x10080
	global_load_lds_dwordx4 v[0:1], off
	v_lshl_add_u64 v[0:1], v[2:3], 0, s[12:13]
	s_mov_b32 m0, s59
	s_addc_u32 s15, s27, 0
	global_load_lds_dwordx4 v[0:1], off
	s_add_i32 m0, s51, 0x1c000
	v_lshl_add_u64 v[0:1], s[14:15], 0, v[130:131]
	global_load_lds_dwordx4 v[0:1], off
	v_lshl_add_u64 v[0:1], s[14:15], 0, v[134:135]
	s_add_i32 m0, s51, 0x1e000
	v_and_b32_e32 v2, 15, v8
	global_load_lds_dwordx4 v[0:1], off
	s_waitcnt vmcnt(8)
	s_barrier
	v_lshrrev_b32_e32 v0, 4, v8
	v_bfe_u32 v1, v8, 4, 2
	v_or_b32_e32 v3, s3, v2
	s_sext_i32_i8 s25, s4
	v_lshlrev_b32_e32 v1, 4, v1
	v_lshlrev_b32_e32 v4, 6, v3
	s_movk_i32 s4, 0x3c0
	v_lshlrev_b32_e32 v3, 2, v3
	s_cmpk_lt_u32 s80, 0x100
	v_bfe_u32 v0, v0, 1, 1
	v_readlane_b32 s16, v255, 1
	v_and_or_b32 v4, v4, s4, v1
	v_and_b32_e32 v3, 32, v3
	v_lshlrev_b32_e32 v5, 2, v8
	s_cselect_b64 s[14:15], -1, 0
	v_lshl_or_b32 v0, s33, 1, v0
	s_lshl_b32 s5, s33, 6
	s_ashr_i32 s33, s16, 31
	s_mov_b32 s60, s16
	s_add_i32 s16, s40, 0
	v_bitop3_b32 v3, v4, s42, v3 bitop3:0xde
	v_lshl_or_b32 v4, v2, 6, v1
	v_and_b32_e32 v5, 32, v5
	s_add_i32 s16, s16, 0x20000
	v_bitop3_b32 v146, v4, s41, v5 bitop3:0xde
	v_and_or_b32 v4, v1, 16, v2
	s_add_i32 s5, s5, s16
	s_waitcnt vmcnt(6)
	v_lshlrev_b32_e32 v136, 4, v4
	s_movk_i32 s4, 0x210
	v_mov_b32_e32 v5, s5
	v_mul_u32_u24_e32 v4, 0x210, v0
	v_mad_u32_u24 v2, v2, s4, v5
	v_add_u32_e32 v5, s16, v136
	v_lshlrev_b32_e32 v138, 11, v0
	s_add_i32 s61, 0, 0x10000
	s_add_i32 s62, 0, 0x14000
	v_mov_b32_e32 v137, v131
	v_mov_b32_e32 v139, v131
	v_or_b32_e32 v140, 0x4000, v138
	v_mov_b32_e32 v141, v131
	v_mov_b64_e32 v[142:143], 0x200
	v_mov_b64_e32 v[144:145], 0x1ff
	v_add_u32_e32 v147, s61, v146
	v_add_u32_e32 v148, s62, v146
	v_add_u32_e32 v149, 0, v3
	v_add_u32_e32 v150, v2, v1
	v_add_u32_e32 v151, v5, v4
	s_barrier
	v_readlane_b32 s17, v255, 2
	s_waitcnt vmcnt(0)
	s_branch .LBB0_1270

; #define PG8_STAGE(bufoff, gbase, voff) do { _Pragma("unroll") for (int _i = 0; _i < 2; ++_i) \
;         __builtin_amdgcn_global_load_lds((const unsigned*)((const char*)(gbase) + (voff)[_i]), (LAS unsigned*)(lds + (bufoff) + ldsw + _i * 8192), 16, 0, 0); } while (0)
; #define PG8_WAIT_V(n) asm volatile("s_waitcnt vmcnt(" #n ")" ::: "memory")
; #define PG8_BAR __builtin_amdgcn_s_barrier()
; #define lane lane_id()
; template <class Epi, class Sched>
; __device__ __forceinline__ void gemm_phase(LAS unsigned char* lds, const Gemm g, const Sched& S, const Epi& E, int wave_id) {
;     ...
;     const int wid = wave_id, lane = tid & 63, wr = wid >> 2, wc = wid & 3, fr = lane & 15, fq = lane >> 4;
;     const int K = g.K, nt = K / BK;
;     unsigned voffA[2], voffB[2];
; #pragma unroll
;     for (int i = 0; i < 2; ++i) { int R, C; stage_rc(tid * 16 + i * 8192, R, C); const int Rb = (R & ~31) + perm32(R & 31);
;         voffA[i] = (unsigned)(R * g.lda + C) * 2u; voffB[i] = (unsigned)(Rb * g.ldb + C) * 2u; }
;     const size_t kstep = (size_t)(BK * 2);
;     const size_t hstepA = (size_t)HALF * g.lda * 2, hstepB = (size_t)HALF * g.ldb * 2;
;     const size_t tstepA = 2 * hstepA, tstepB = 2 * hstepB;
;     const unsigned ldsw = (unsigned)wid * 1024u;
;     const int aoff = lds_byte(wr * 64 + fr, fq * 8), boff = lds_byte(wc * 32 + fr, fq * 8);
;     ...
;     PG8_STAGE(PG8_SB(0, 0), cB, voffB); PG8_STAGE(PG8_SB(0, 1), cB + hstepB, voffB); PG8_STAGE(PG8_SA(0, 0), cA, voffA); PG8_STAGE(PG8_SA(0, 1), cA + hstepA, voffA);
;     if (wr == 1) PG8_BAR;
;     PG8_WAIT_V(2); PG8_BAR;
;     PG8_STAGE(PG8_SB(1, 0), cB + kstep, voffB); PG8_STAGE(PG8_SA(1, 0), cA + kstep, voffA); PG8_STAGE(PG8_SB(1, 1), cB + hstepB + kstep, voffB);
;     PG8_WAIT_V(6); PG8_BAR;
.LBB0_1372:
	s_mov_b64 s[22:23], 0x80
	s_bfe_u32 s18, s80, 0x20006
	s_add_i32 m0, s37, 0x18000
	v_lshl_add_u64 v[6:7], v[6:7], 0, s[22:23]
	s_lshl_b32 s5, s6, 13
	s_lshl_b32 s36, s18, 5
	s_lshl_b32 s7, s18, 12
	global_load_lds_dwordx4 v[6:7], off
	v_lshl_add_u64 v[4:5], v[4:5], 0, s[22:23]
	s_add_i32 m0, s37, 0x1a000
	s_add_i32 s55, s37, 0x8000
	s_add_i32 s56, s37, 0xa000
	global_load_lds_dwordx4 v[4:5], off
	v_lshl_add_u64 v[0:1], v[0:1], 0, s[22:23]
	s_mov_b32 m0, s55
	s_add_u32 s8, s46, 0x40080
	global_load_lds_dwordx4 v[0:1], off
	v_lshl_add_u64 v[0:1], v[2:3], 0, s[22:23]
	s_mov_b32 m0, s56
	s_addc_u32 s9, s47, 0
	global_load_lds_dwordx4 v[0:1], off
	s_add_i32 m0, s37, 0x1c000
	v_lshl_add_u64 v[0:1], s[8:9], 0, v[154:155]
	global_load_lds_dwordx4 v[0:1], off
	v_lshl_add_u64 v[0:1], s[8:9], 0, v[158:159]
	s_add_i32 m0, s37, 0x1e000
	v_bfe_u32 v2, v9, 4, 2
	global_load_lds_dwordx4 v[0:1], off
	s_waitcnt vmcnt(8)
	s_barrier
	v_and_b32_e32 v1, 15, v9
	s_cmpk_lt_u32 s80, 0x100
	v_readlane_b32 s8, v255, 1
	v_lshl_or_b32 v163, s6, 6, v1
	v_lshlrev_b32_e32 v3, 4, v2
	v_lshlrev_b32_e32 v4, 2, v9
	s_cselect_b64 s[24:25], -1, 0
	s_or_b32 s6, s18, s6
	s_ashr_i32 s57, s8, 31
	s_mov_b32 s58, s8
	s_lshl_b32 s8, s18, 7
	v_lshl_or_b32 v3, v1, 6, v3
	v_and_b32_e32 v4, 32, v4
	v_or3_b32 v1, s6, v1, v2
	v_readlane_b32 s9, v255, 2
	s_add_u32 s8, s68, s8
	v_bitop3_b32 v165, v3, s7, v4 bitop3:0xde
	v_cmp_eq_u32_e64 s[6:7], 0, v1
	s_addc_u32 s9, s69, 0
	v_lshlrev_b32_e32 v1, 14, v8
	s_add_u32 s26, s92, 0x1f440000
	v_and_b32_e32 v1, 0xffff8000, v1
	s_sext_i32_i8 s11, s4
	v_lshlrev_b32_e32 v0, 3, v2
	v_bitop3_b32 v5, v3, s5, v4 bitop3:0xde
	v_cmp_eq_u32_e64 s[4:5], 0, v2
	v_lshlrev_b32_e32 v160, 5, v2
	s_addc_u32 s27, s93, 0
	v_lshl_add_u32 v1, v10, 11, v1
	v_and_b32_e32 v2, 1, v8
	s_add_u32 s28, s92, 0x13400000
	v_lshl_or_b32 v1, v2, 6, v1
	s_addc_u32 s29, s93, 0
	v_lshl_add_u32 v168, v11, 1, v1
	v_lshlrev_b32_e32 v1, 14, v12
	s_add_u32 s30, s92, 0x1f480000
	v_and_b32_e32 v1, 0xffff8000, v1
	s_addc_u32 s31, s93, 0
	v_lshl_add_u32 v1, v13, 11, v1
	v_and_b32_e32 v2, 1, v12
	s_waitcnt vmcnt(6)
	s_add_u32 s59, s92, 0x1f604000
	v_lshl_or_b32 v1, v2, 6, v1
	v_or_b32_e32 v162, s36, v0
	s_addc_u32 s60, s93, 0
	v_lshl_add_u32 v170, v14, 1, v1
	s_add_i32 s61, 0, 0x10000
	s_add_i32 s62, 0, 0x14000
	v_mbcnt_lo_u32_b32 v1, -1, 0
	v_or_b32_e32 v164, 0x80, v162
	v_lshl_add_u64 v[166:167], s[8:9], 0, v[160:161]
	v_mov_b32_e32 v169, v161
	v_mov_b32_e32 v171, v161
	v_mov_b64_e32 v[172:173], 0x200
	v_mov_b64_e32 v[174:175], 0x1ff
	v_add_u32_e32 v200, s61, v165
	v_add_u32_e32 v201, s62, v165
	v_add_u32_e32 v202, 0, v5
	v_mbcnt_hi_u32_b32 v203, -1, v1
	v_mov_b32_e32 v204, 0x358637bd
	s_mov_b32 s34, 0x3a800000
	s_mov_b32 s63, 0x800000
	s_lshl_b32 s18, s36, 2
	v_lshlrev_b32_e32 v160, 2, v0
	s_mov_b32 s36, 0x358637bd
	s_mov_b32 s64, s19
	s_barrier
	s_branch .LBB0_1375
